# dropped hipcc's vmcnt(0) drain in front of each unit's K-loop (only stores and LDS-DMA are outstanding there)
# speedup vs baseline: 1.0010x; 1.0010x over previous
;     __host__ __device__ bool next(int i, Unit& u) const { const int idx = first + i; if (idx >= last) return false; u.pm = idx >> 2; u.pn = idx & 3; return true; }
; template <class Epi, class Sched, bool ALIGN_EPI = false, bool SP2 = false>
; __device__ __forceinline__ void gemm_phase(PG8_LAS unsigned char* lds, const Gemm g, const Sched& S, const Epi& E) {
;     ...
;     for (;;) {
;         const bool has_next = S.next(ui + 1, nxt);
;         const char* nA = has_next ? (const char*)g.A + (size_t)nxt.pm * tstep : cA; const char* nB = has_next ? (const char*)g.Bt + (size_t)nxt.pn * tstep : cB;
;         asm volatile(".p2align 8");
;         for (int t = 0; t < nt; t += 2) {
;     ...
; #pragma unroll
;         for (int a = 0; a < 2; ++a)
; #pragma unroll
;             for (int b = 0; b < 2; ++b)
; #pragma unroll
;                 for (int m = 0; m < 4; ++m)
; #pragma unroll
;                     for (int n = 0; n < 2; ++n) acc[a][b][m][n] = (f32x4){0.f, 0.f, 0.f, 0.f};
;         cur = nxt; cA = nA; cB = nB; ++ui;
.LBB0_262:
	v_mov_b64_e32 v[0:1], 0
	v_mov_b64_e32 v[2:3], 0
	v_mov_b64_e32 v[4:5], 0
	v_mov_b64_e32 v[6:7], 0
	v_mov_b64_e32 v[8:9], 0
	v_mov_b64_e32 v[10:11], 0
	v_mov_b64_e32 v[12:13], 0
	v_mov_b64_e32 v[14:15], 0
	v_mov_b64_e32 v[16:17], 0
	v_mov_b64_e32 v[18:19], 0
	v_mov_b64_e32 v[20:21], 0
	v_mov_b64_e32 v[22:23], 0
	v_mov_b64_e32 v[24:25], 0
	v_mov_b64_e32 v[26:27], 0
	v_mov_b64_e32 v[28:29], 0
	v_mov_b64_e32 v[30:31], 0
	v_mov_b64_e32 v[32:33], 0
	v_mov_b64_e32 v[34:35], 0
	v_mov_b64_e32 v[36:37], 0
	v_mov_b64_e32 v[38:39], 0
	v_mov_b64_e32 v[40:41], 0
	v_mov_b64_e32 v[42:43], 0
	v_mov_b64_e32 v[44:45], 0
	v_mov_b64_e32 v[46:47], 0
	v_mov_b64_e32 v[48:49], 0
	v_mov_b64_e32 v[50:51], 0
	v_mov_b64_e32 v[52:53], 0
	v_mov_b64_e32 v[54:55], 0
	v_mov_b64_e32 v[56:57], 0
	v_mov_b64_e32 v[58:59], 0
	v_mov_b64_e32 v[60:61], 0
	v_mov_b64_e32 v[62:63], 0
	v_mov_b64_e32 v[64:65], 0
	v_mov_b64_e32 v[66:67], 0
	v_mov_b64_e32 v[68:69], 0
	v_mov_b64_e32 v[70:71], 0
	v_mov_b64_e32 v[72:73], 0
	v_mov_b64_e32 v[74:75], 0
	v_mov_b64_e32 v[76:77], 0
	v_mov_b64_e32 v[78:79], 0
	v_mov_b64_e32 v[80:81], 0
	v_mov_b64_e32 v[82:83], 0
	v_mov_b64_e32 v[84:85], 0
	v_mov_b64_e32 v[86:87], 0
	v_mov_b64_e32 v[88:89], 0
	v_mov_b64_e32 v[90:91], 0
	v_mov_b64_e32 v[92:93], 0
	v_mov_b64_e32 v[94:95], 0
	v_mov_b64_e32 v[96:97], 0
	v_mov_b64_e32 v[98:99], 0
	v_mov_b64_e32 v[100:101], 0
	v_mov_b64_e32 v[102:103], 0
	v_mov_b64_e32 v[104:105], 0
	v_mov_b64_e32 v[106:107], 0
	v_mov_b64_e32 v[108:109], 0
	v_mov_b64_e32 v[110:111], 0
	v_mov_b64_e32 v[112:113], 0
	v_mov_b64_e32 v[114:115], 0
	v_mov_b64_e32 v[116:117], 0
	v_mov_b64_e32 v[118:119], 0
	v_mov_b64_e32 v[120:121], 0
	v_mov_b64_e32 v[122:123], 0
	v_mov_b64_e32 v[124:125], 0
	v_mov_b64_e32 v[126:127], 0
	s_andn2_b64 vcc, exec, s[20:21]
	s_waitcnt lgkmcnt(0)
	.p2align 8
	s_cbranch_vccnz .LBB0_265
	s_add_u32 s40, s40, 0x80
	s_addc_u32 s41, s41, 0
	s_add_u32 s33, s42, 0x100
	s_addc_u32 s38, s43, 0
	s_mov_b32 s42, 0

;     __host__ __device__ bool next(int i, Unit& u) const { const int idx = first + i; if (idx >= last) return false; u.pm = idx >> 2; u.pn = idx & 3; return true; }
; template <class Epi, class Sched, bool ALIGN_EPI = false, bool SP2 = false>
; __device__ __forceinline__ void gemm_phase(PG8_LAS unsigned char* lds, const Gemm g, const Sched& S, const Epi& E) {
;     ...
;     for (;;) {
;         const bool has_next = S.next(ui + 1, nxt);
;         const char* nA = has_next ? (const char*)g.A + (size_t)nxt.pm * tstep : cA; const char* nB = has_next ? (const char*)g.Bt + (size_t)nxt.pn * tstep : cB;
;         asm volatile(".p2align 8");
;         for (int t = 0; t < nt; t += 2) {
;     ...
; #pragma unroll
;         for (int a = 0; a < 2; ++a)
; #pragma unroll
;             for (int b = 0; b < 2; ++b)
; #pragma unroll
;                 for (int m = 0; m < 4; ++m)
; #pragma unroll
;                     for (int n = 0; n < 2; ++n) acc[a][b][m][n] = (f32x4){0.f, 0.f, 0.f, 0.f};
;         cur = nxt; cA = nA; cB = nB; ++ui;
.LBB0_471:
	v_mov_b64_e32 v[0:1], 0
	v_mov_b64_e32 v[2:3], 0
	v_mov_b64_e32 v[4:5], 0
	v_mov_b64_e32 v[6:7], 0
	v_mov_b64_e32 v[8:9], 0
	v_mov_b64_e32 v[10:11], 0
	v_mov_b64_e32 v[12:13], 0
	v_mov_b64_e32 v[14:15], 0
	v_mov_b64_e32 v[16:17], 0
	v_mov_b64_e32 v[18:19], 0
	v_mov_b64_e32 v[20:21], 0
	v_mov_b64_e32 v[22:23], 0
	v_mov_b64_e32 v[24:25], 0
	v_mov_b64_e32 v[26:27], 0
	v_mov_b64_e32 v[28:29], 0
	v_mov_b64_e32 v[30:31], 0
	v_mov_b64_e32 v[32:33], 0
	v_mov_b64_e32 v[34:35], 0
	v_mov_b64_e32 v[36:37], 0
	v_mov_b64_e32 v[38:39], 0
	v_mov_b64_e32 v[40:41], 0
	v_mov_b64_e32 v[42:43], 0
	v_mov_b64_e32 v[44:45], 0
	v_mov_b64_e32 v[46:47], 0
	v_mov_b64_e32 v[48:49], 0
	v_mov_b64_e32 v[50:51], 0
	v_mov_b64_e32 v[52:53], 0
	v_mov_b64_e32 v[54:55], 0
	v_mov_b64_e32 v[56:57], 0
	v_mov_b64_e32 v[58:59], 0
	v_mov_b64_e32 v[60:61], 0
	v_mov_b64_e32 v[62:63], 0
	v_mov_b64_e32 v[64:65], 0
	v_mov_b64_e32 v[66:67], 0
	v_mov_b64_e32 v[68:69], 0
	v_mov_b64_e32 v[70:71], 0
	v_mov_b64_e32 v[72:73], 0
	v_mov_b64_e32 v[74:75], 0
	v_mov_b64_e32 v[76:77], 0
	v_mov_b64_e32 v[78:79], 0
	v_mov_b64_e32 v[80:81], 0
	v_mov_b64_e32 v[82:83], 0
	v_mov_b64_e32 v[84:85], 0
	v_mov_b64_e32 v[86:87], 0
	v_mov_b64_e32 v[88:89], 0
	v_mov_b64_e32 v[90:91], 0
	v_mov_b64_e32 v[92:93], 0
	v_mov_b64_e32 v[94:95], 0
	v_mov_b64_e32 v[96:97], 0
	v_mov_b64_e32 v[98:99], 0
	v_mov_b64_e32 v[100:101], 0
	v_mov_b64_e32 v[102:103], 0
	v_mov_b64_e32 v[104:105], 0
	v_mov_b64_e32 v[106:107], 0
	v_mov_b64_e32 v[108:109], 0
	v_mov_b64_e32 v[110:111], 0
	v_mov_b64_e32 v[112:113], 0
	v_mov_b64_e32 v[114:115], 0
	v_mov_b64_e32 v[116:117], 0
	v_mov_b64_e32 v[118:119], 0
	v_mov_b64_e32 v[120:121], 0
	v_mov_b64_e32 v[122:123], 0
	v_mov_b64_e32 v[124:125], 0
	v_mov_b64_e32 v[126:127], 0
	s_andn2_b64 vcc, exec, s[56:57]
	s_waitcnt lgkmcnt(0)
	.p2align 8
	s_cbranch_vccnz .LBB0_474
	s_add_u32 s10, s14, 0x80
	s_addc_u32 s11, s15, 0
	s_add_u32 s5, s12, 0x100
	s_addc_u32 s14, s13, 0
	s_mov_b32 s12, 0
